# th13 minus 35 compiler pads (s_nop 0 after v_pk_fma_f32, a VOP3P op_sel_hi false positive) in the GEMM2 residual epilogue
# speedup vs baseline: 1.0043x; 1.0020x over previous
.LBB0_835:
	v_and_b32_e32 v153, 64, v208
	v_xor_b32_e32 v152, 16, v208
	v_add_u32_e32 v154, 64, v153
	v_cmp_lt_i32_e32 vcc, v152, v154
	v_lshl_add_u32 v151, s6, 8, v146
	v_lshl_or_b32 v2, s17, 9, v149
	v_readlane_b32 s2, v254, 39
	v_cndmask_b32_e32 v152, v208, v152, vcc
	v_lshl_add_u32 v2, v151, 12, v2
	v_and_b32_e32 v228, -16, v151
	v_lshlrev_b32_e32 v228, 12, v228
	v_lshrrev_b32_e32 v229, 6, v149
	v_lshlrev_b32_e32 v229, 10, v229
	v_lshl_or_b32 v229, s17, 13, v229
	v_and_b32_e32 v230, 15, v151
	v_lshl_or_b32 v229, v230, 6, v229
	v_bfe_u32 v230, v149, 4, 2
	v_lshrrev_b32_e32 v231, 2, v151
	v_and_b32_e32 v231, 2, v231
	v_xor_b32_e32 v230, v230, v231
	v_lshl_or_b32 v229, v230, 4, v229
	v_add_u32_e32 v229, 0x800, v229
	v_add_u32_e32 v2, v228, v229
	v_readlane_b32 s3, v254, 40
	v_lshlrev_b32_e32 v153, 2, v152
	v_xor_b32_e32 v152, 32, v208
	v_cmp_lt_i32_e32 vcc, v152, v154
	s_nop 1
	global_load_dwordx4 v[154:157], v2, s[2:3] offset:-2048
	global_load_dwordx4 v[158:161], v2, s[2:3] offset:2048
	v_lshl_add_u64 v[144:145], s[2:3], 0, v[2:3]
	v_cndmask_b32_e32 v152, v208, v152, vcc
	v_lshlrev_b32_e32 v152, 2, v152
	s_mov_b32 s99, 0
	s_mov_b32 s98, 0x10000
	v_lshl_add_u64 v[228:229], v[144:145], 0, s[98:99]
	global_load_dwordx4 v[168:171], v[228:229], off offset:2048
	global_load_dwordx4 v[172:175], v[228:229], off offset:-2048
	s_mov_b32 s98, 0x20000
	v_lshl_add_u64 v[230:231], v[144:145], 0, s[98:99]
	global_load_dwordx4 v[176:179], v[230:231], off offset:2048
	global_load_dwordx4 v[180:183], v[230:231], off offset:-2048
	s_mov_b32 s98, 0x30000
	v_lshl_add_u64 v[232:233], v[144:145], 0, s[98:99]
	global_load_dwordx4 v[184:187], v[232:233], off offset:2048
	global_load_dwordx4 v[188:191], v[232:233], off offset:-2048
	s_mov_b32 s98, 0x80000
	v_lshl_add_u64 v[234:235], v[144:145], 0, s[98:99]
	global_load_dwordx4 v[192:195], v[234:235], off offset:-2048
	global_load_dwordx4 v[196:199], v[234:235], off offset:2048
	s_mov_b32 s98, 0x90000
	v_lshl_add_u64 v[236:237], v[144:145], 0, s[98:99]
	global_load_dwordx4 v[200:203], v[236:237], off offset:2048
	global_load_dwordx4 v[204:207], v[236:237], off offset:-2048
	s_mov_b32 s98, 0xa0000
	v_lshl_add_u64 v[238:239], v[144:145], 0, s[98:99]
	global_load_dwordx4 v[212:215], v[238:239], off offset:2048
	global_load_dwordx4 v[216:219], v[238:239], off offset:-2048
	s_mov_b32 s98, 0xb0000
	v_lshl_add_u64 v[240:241], v[144:145], 0, s[98:99]
	global_load_dwordx4 v[220:223], v[240:241], off offset:2048
	global_load_dwordx4 v[224:227], v[240:241], off offset:-2048
	s_waitcnt vmcnt(14)
	v_lshlrev_b32_e32 v162, 16, v154
	v_and_b32_e32 v163, 0xffff0000, v154
	v_pk_fma_f32 v[162:163], v[128:129], s[14:15], v[162:163]
	v_lshlrev_b32_e32 v154, 16, v155
	v_cvt_pk_bf16_f32 v128, v162, v163
	v_fma_f32 v162, v162, v162, 0
	v_and_b32_e32 v155, 0xffff0000, v155
	v_fmac_f32_e32 v162, v163, v163
	v_pk_fma_f32 v[130:131], v[130:131], s[14:15], v[154:155]
	v_fmac_f32_e32 v162, v130, v130
	v_cvt_pk_bf16_f32 v129, v130, v131
	v_fmac_f32_e32 v162, v131, v131
	v_lshlrev_b32_e32 v130, 16, v156
	v_and_b32_e32 v131, 0xffff0000, v156
	v_pk_fma_f32 v[124:125], v[124:125], s[14:15], v[130:131]
	v_fmac_f32_e32 v162, v124, v124
	v_cvt_pk_bf16_f32 v130, v124, v125
	v_fmac_f32_e32 v162, v125, v125
	v_lshlrev_b32_e32 v124, 16, v157
	v_and_b32_e32 v125, 0xffff0000, v157
	v_pk_fma_f32 v[124:125], v[126:127], s[14:15], v[124:125]
	v_fmac_f32_e32 v162, v124, v124
	v_cvt_pk_bf16_f32 v131, v124, v125
	v_fmac_f32_e32 v162, v125, v125
	v_lshlrev_b32_e32 v124, 16, v158
	v_and_b32_e32 v125, 0xffff0000, v158
	v_pk_fma_f32 v[124:125], v[120:121], s[14:15], v[124:125]
	v_fmac_f32_e32 v162, v124, v124
	v_cvt_pk_bf16_f32 v120, v124, v125
	v_fmac_f32_e32 v162, v125, v125
	v_lshlrev_b32_e32 v124, 16, v159
	v_and_b32_e32 v125, 0xffff0000, v159
	v_pk_fma_f32 v[122:123], v[122:123], s[14:15], v[124:125]
	v_fmac_f32_e32 v162, v122, v122
	v_cvt_pk_bf16_f32 v121, v122, v123
	v_fmac_f32_e32 v162, v123, v123
	v_lshlrev_b32_e32 v122, 16, v160
	v_and_b32_e32 v123, 0xffff0000, v160
	v_pk_fma_f32 v[116:117], v[116:117], s[14:15], v[122:123]
	v_fmac_f32_e32 v162, v116, v116
	v_cvt_pk_bf16_f32 v122, v116, v117
	v_fmac_f32_e32 v162, v117, v117
	v_lshlrev_b32_e32 v116, 16, v161
	v_and_b32_e32 v117, 0xffff0000, v161
	v_pk_fma_f32 v[116:117], v[118:119], s[14:15], v[116:117]
	v_fmac_f32_e32 v162, v116, v116
	v_fmac_f32_e32 v162, v117, v117
	v_cvt_pk_bf16_f32 v123, v116, v117
	global_store_dwordx4 v2, v[128:131], s[2:3] offset:-2048
	global_store_dwordx4 v2, v[120:123], s[2:3] offset:2048
	ds_bpermute_b32 v2, v153, v162
	s_mov_b32 s2, 0x10000
	v_add_co_u32_e32 v124, vcc, s2, v144
	s_mov_b32 s2, 0x20000
	s_waitcnt lgkmcnt(0)
	v_add_f32_e32 v2, v162, v2
	ds_bpermute_b32 v116, v152, v2
	v_addc_co_u32_e32 v125, vcc, 0, v145, vcc
	s_waitcnt lgkmcnt(0)
	v_add_f32_e32 v2, v2, v116
	s_waitcnt vmcnt(14)
	v_lshlrev_b32_e32 v126, 16, v172
	v_and_b32_e32 v127, 0xffff0000, v172
	v_pk_fma_f32 v[126:127], v[112:113], s[14:15], v[126:127]
	v_lshlrev_b32_e32 v120, 16, v173
	v_cvt_pk_bf16_f32 v112, v126, v127
	v_fma_f32 v126, v126, v126, 0
	v_and_b32_e32 v121, 0xffff0000, v173
	v_fmac_f32_e32 v126, v127, v127
	v_pk_fma_f32 v[114:115], v[114:115], s[14:15], v[120:121]
	v_fmac_f32_e32 v126, v114, v114
	v_cvt_pk_bf16_f32 v113, v114, v115
	v_fmac_f32_e32 v126, v115, v115
	v_lshlrev_b32_e32 v114, 16, v174
	v_and_b32_e32 v115, 0xffff0000, v174
	v_pk_fma_f32 v[108:109], v[108:109], s[14:15], v[114:115]
	v_fmac_f32_e32 v126, v108, v108
	v_cvt_pk_bf16_f32 v114, v108, v109
	v_fmac_f32_e32 v126, v109, v109
	v_lshlrev_b32_e32 v108, 16, v175
	v_and_b32_e32 v109, 0xffff0000, v175
	v_pk_fma_f32 v[108:109], v[110:111], s[14:15], v[108:109]
	v_add_co_u32_e32 v110, vcc, s2, v144
	v_fmac_f32_e32 v126, v108, v108
	v_cvt_pk_bf16_f32 v115, v108, v109
	v_fmac_f32_e32 v126, v109, v109
	v_lshlrev_b32_e32 v108, 16, v168
	v_and_b32_e32 v109, 0xffff0000, v168
	v_pk_fma_f32 v[108:109], v[104:105], s[14:15], v[108:109]
	v_addc_co_u32_e32 v111, vcc, 0, v145, vcc
	v_fmac_f32_e32 v126, v108, v108
	v_cvt_pk_bf16_f32 v104, v108, v109
	v_fmac_f32_e32 v126, v109, v109
	v_lshlrev_b32_e32 v108, 16, v169
	v_and_b32_e32 v109, 0xffff0000, v169
	v_pk_fma_f32 v[106:107], v[106:107], s[14:15], v[108:109]
	s_mov_b32 s2, 0x30000
	v_fmac_f32_e32 v126, v106, v106
	v_cvt_pk_bf16_f32 v105, v106, v107
	v_fmac_f32_e32 v126, v107, v107
	v_lshlrev_b32_e32 v106, 16, v170
	v_and_b32_e32 v107, 0xffff0000, v170
	v_pk_fma_f32 v[100:101], v[100:101], s[14:15], v[106:107]
	v_fmac_f32_e32 v126, v100, v100
	v_cvt_pk_bf16_f32 v106, v100, v101
	v_fmac_f32_e32 v126, v101, v101
	v_lshlrev_b32_e32 v100, 16, v171
	v_and_b32_e32 v101, 0xffff0000, v171
	v_pk_fma_f32 v[100:101], v[102:103], s[14:15], v[100:101]
	s_nop 0
	v_cvt_pk_bf16_f32 v107, v100, v101
	global_store_dwordx4 v[124:125], v[112:115], off offset:-2048
	global_store_dwordx4 v[124:125], v[104:107], off offset:2048
	s_nop 0
	v_fmac_f32_e32 v126, v100, v100
	v_fmac_f32_e32 v126, v101, v101
	ds_bpermute_b32 v100, v153, v126
	s_waitcnt lgkmcnt(0)
	v_add_f32_e32 v100, v126, v100
	ds_bpermute_b32 v101, v152, v100
	s_waitcnt vmcnt(14)
	v_lshlrev_b32_e32 v112, 16, v180
	v_and_b32_e32 v113, 0xffff0000, v180
	v_pk_fma_f32 v[112:113], v[96:97], s[14:15], v[112:113]
	v_lshlrev_b32_e32 v106, 16, v181
	v_cvt_pk_bf16_f32 v96, v112, v113
	v_fma_f32 v112, v112, v112, 0
	v_and_b32_e32 v107, 0xffff0000, v181
	v_fmac_f32_e32 v112, v113, v113
	v_pk_fma_f32 v[98:99], v[98:99], s[14:15], v[106:107]
	v_fmac_f32_e32 v112, v98, v98
	v_cvt_pk_bf16_f32 v97, v98, v99
	v_fmac_f32_e32 v112, v99, v99
	v_lshlrev_b32_e32 v98, 16, v182
	v_and_b32_e32 v99, 0xffff0000, v182
	v_pk_fma_f32 v[92:93], v[92:93], s[14:15], v[98:99]
	v_fmac_f32_e32 v112, v92, v92
	v_cvt_pk_bf16_f32 v98, v92, v93
	v_fmac_f32_e32 v112, v93, v93
	v_lshlrev_b32_e32 v92, 16, v183
	v_and_b32_e32 v93, 0xffff0000, v183
	v_pk_fma_f32 v[92:93], v[94:95], s[14:15], v[92:93]
	v_fmac_f32_e32 v112, v92, v92
	v_cvt_pk_bf16_f32 v99, v92, v93
	v_fmac_f32_e32 v112, v93, v93
	v_lshlrev_b32_e32 v92, 16, v176
	v_and_b32_e32 v93, 0xffff0000, v176
	v_pk_fma_f32 v[92:93], v[88:89], s[14:15], v[92:93]
	v_fmac_f32_e32 v112, v92, v92
	v_cvt_pk_bf16_f32 v88, v92, v93
	v_fmac_f32_e32 v112, v93, v93
	v_lshlrev_b32_e32 v92, 16, v177
	v_and_b32_e32 v93, 0xffff0000, v177
	v_pk_fma_f32 v[90:91], v[90:91], s[14:15], v[92:93]
	v_add_co_u32_e32 v92, vcc, s2, v144
	v_fmac_f32_e32 v112, v90, v90
	v_cvt_pk_bf16_f32 v89, v90, v91
	v_fmac_f32_e32 v112, v91, v91
	v_lshlrev_b32_e32 v90, 16, v178
	v_and_b32_e32 v91, 0xffff0000, v178
	v_pk_fma_f32 v[84:85], v[84:85], s[14:15], v[90:91]
	v_addc_co_u32_e32 v93, vcc, 0, v145, vcc
	v_fmac_f32_e32 v112, v84, v84
	v_cvt_pk_bf16_f32 v90, v84, v85
	v_fmac_f32_e32 v112, v85, v85
	v_lshlrev_b32_e32 v84, 16, v179
	v_and_b32_e32 v85, 0xffff0000, v179
	v_pk_fma_f32 v[84:85], v[86:87], s[14:15], v[84:85]
	s_mov_b32 s2, 0x80000
	v_fmac_f32_e32 v112, v84, v84
	v_fmac_f32_e32 v112, v85, v85
	v_cvt_pk_bf16_f32 v91, v84, v85
	ds_bpermute_b32 v84, v153, v112
	global_store_dwordx4 v[110:111], v[96:99], off offset:-2048
	global_store_dwordx4 v[110:111], v[88:91], off offset:2048
	s_waitcnt lgkmcnt(0)
	v_add_f32_e32 v94, v112, v84
	ds_bpermute_b32 v95, v152, v94
	s_waitcnt vmcnt(14)
	v_lshlrev_b32_e32 v96, 16, v188
	v_and_b32_e32 v97, 0xffff0000, v188
	v_pk_fma_f32 v[96:97], v[80:81], s[14:15], v[96:97]
	v_lshlrev_b32_e32 v88, 16, v189
	v_cvt_pk_bf16_f32 v80, v96, v97
	v_fma_f32 v96, v96, v96, 0
	v_and_b32_e32 v89, 0xffff0000, v189
	v_fmac_f32_e32 v96, v97, v97
	v_pk_fma_f32 v[82:83], v[82:83], s[14:15], v[88:89]
	v_fmac_f32_e32 v96, v82, v82
	v_cvt_pk_bf16_f32 v81, v82, v83
	v_fmac_f32_e32 v96, v83, v83
	v_lshlrev_b32_e32 v82, 16, v190
	v_and_b32_e32 v83, 0xffff0000, v190
	v_pk_fma_f32 v[76:77], v[76:77], s[14:15], v[82:83]
	v_fmac_f32_e32 v96, v76, v76
	v_cvt_pk_bf16_f32 v82, v76, v77
	v_fmac_f32_e32 v96, v77, v77
	v_lshlrev_b32_e32 v76, 16, v191
	v_and_b32_e32 v77, 0xffff0000, v191
	v_pk_fma_f32 v[76:77], v[78:79], s[14:15], v[76:77]
	v_add_co_u32_e32 v78, vcc, s2, v144
	v_fmac_f32_e32 v96, v76, v76
	v_cvt_pk_bf16_f32 v83, v76, v77
	v_fmac_f32_e32 v96, v77, v77
	v_lshlrev_b32_e32 v76, 16, v184
	v_and_b32_e32 v77, 0xffff0000, v184
	v_pk_fma_f32 v[76:77], v[72:73], s[14:15], v[76:77]
	v_addc_co_u32_e32 v79, vcc, 0, v145, vcc
	v_fmac_f32_e32 v96, v76, v76
	v_cvt_pk_bf16_f32 v72, v76, v77
	v_fmac_f32_e32 v96, v77, v77
	v_lshlrev_b32_e32 v76, 16, v185
	v_and_b32_e32 v77, 0xffff0000, v185
	v_pk_fma_f32 v[74:75], v[74:75], s[14:15], v[76:77]
	s_mov_b32 s2, 0x90000
	v_fmac_f32_e32 v96, v74, v74
	v_cvt_pk_bf16_f32 v73, v74, v75
	v_fmac_f32_e32 v96, v75, v75
	v_lshlrev_b32_e32 v74, 16, v186
	v_and_b32_e32 v75, 0xffff0000, v186
	v_pk_fma_f32 v[68:69], v[68:69], s[14:15], v[74:75]
	v_fmac_f32_e32 v96, v68, v68
	v_cvt_pk_bf16_f32 v74, v68, v69
	v_fmac_f32_e32 v96, v69, v69
	v_lshlrev_b32_e32 v68, 16, v187
	v_and_b32_e32 v69, 0xffff0000, v187
	v_pk_fma_f32 v[68:69], v[70:71], s[14:15], v[68:69]
	s_nop 0
	v_cvt_pk_bf16_f32 v75, v68, v69
	global_store_dwordx4 v[92:93], v[80:83], off offset:-2048
	global_store_dwordx4 v[92:93], v[72:75], off offset:2048
	v_fmac_f32_e32 v96, v68, v68
	v_fmac_f32_e32 v96, v69, v69
	ds_bpermute_b32 v68, v153, v96
	s_waitcnt lgkmcnt(0)
	v_add_f32_e32 v68, v96, v68
	ds_bpermute_b32 v69, v152, v68
	s_waitcnt vmcnt(15)
	v_lshlrev_b32_e32 v80, 16, v192
	v_and_b32_e32 v81, 0xffff0000, v192
	v_pk_fma_f32 v[80:81], v[64:65], s[14:15], v[80:81]
	v_lshlrev_b32_e32 v70, 16, v193
	v_cvt_pk_bf16_f32 v64, v80, v81
	v_fma_f32 v80, v80, v80, 0
	v_and_b32_e32 v71, 0xffff0000, v193
	v_fmac_f32_e32 v80, v81, v81
	v_pk_fma_f32 v[66:67], v[66:67], s[14:15], v[70:71]
	v_fmac_f32_e32 v80, v66, v66
	v_cvt_pk_bf16_f32 v65, v66, v67
	v_fmac_f32_e32 v80, v67, v67
	v_lshlrev_b32_e32 v66, 16, v194
	v_and_b32_e32 v67, 0xffff0000, v194
	v_pk_fma_f32 v[60:61], v[60:61], s[14:15], v[66:67]
	v_fmac_f32_e32 v80, v60, v60
	v_cvt_pk_bf16_f32 v66, v60, v61
	v_fmac_f32_e32 v80, v61, v61
	v_lshlrev_b32_e32 v60, 16, v195
	v_and_b32_e32 v61, 0xffff0000, v195
	v_pk_fma_f32 v[60:61], v[62:63], s[14:15], v[60:61]
	v_add_co_u32_e32 v62, vcc, s2, v144
	v_fmac_f32_e32 v80, v60, v60
	v_cvt_pk_bf16_f32 v67, v60, v61
	v_fmac_f32_e32 v80, v61, v61
	s_waitcnt vmcnt(14)
	v_lshlrev_b32_e32 v60, 16, v196
	v_and_b32_e32 v61, 0xffff0000, v196
	v_pk_fma_f32 v[60:61], v[56:57], s[14:15], v[60:61]
	v_addc_co_u32_e32 v63, vcc, 0, v145, vcc
	v_fmac_f32_e32 v80, v60, v60
	v_cvt_pk_bf16_f32 v56, v60, v61
	v_fmac_f32_e32 v80, v61, v61
	v_lshlrev_b32_e32 v60, 16, v197
	v_and_b32_e32 v61, 0xffff0000, v197
	v_pk_fma_f32 v[58:59], v[58:59], s[14:15], v[60:61]
	s_mov_b32 s2, 0xa0000
	v_fmac_f32_e32 v80, v58, v58
	v_cvt_pk_bf16_f32 v57, v58, v59
	v_fmac_f32_e32 v80, v59, v59
	v_lshlrev_b32_e32 v58, 16, v198
	v_and_b32_e32 v59, 0xffff0000, v198
	v_pk_fma_f32 v[52:53], v[52:53], s[14:15], v[58:59]
	v_fmac_f32_e32 v80, v52, v52
	v_cvt_pk_bf16_f32 v58, v52, v53
	v_fmac_f32_e32 v80, v53, v53
	v_lshlrev_b32_e32 v52, 16, v199
	v_and_b32_e32 v53, 0xffff0000, v199
	v_pk_fma_f32 v[52:53], v[54:55], s[14:15], v[52:53]
	s_nop 0
	v_cvt_pk_bf16_f32 v59, v52, v53
	global_store_dwordx4 v[78:79], v[64:67], off offset:-2048
	global_store_dwordx4 v[78:79], v[56:59], off offset:2048
	s_nop 0
	v_fmac_f32_e32 v80, v52, v52
	v_fmac_f32_e32 v80, v53, v53
	ds_bpermute_b32 v52, v153, v80
	s_waitcnt lgkmcnt(0)
	v_add_f32_e32 v52, v80, v52
	ds_bpermute_b32 v53, v152, v52
	s_waitcnt vmcnt(14)
	v_lshlrev_b32_e32 v64, 16, v204
	v_and_b32_e32 v65, 0xffff0000, v204
	v_pk_fma_f32 v[64:65], v[48:49], s[14:15], v[64:65]
	v_lshlrev_b32_e32 v58, 16, v205
	v_cvt_pk_bf16_f32 v48, v64, v65
	v_fma_f32 v64, v64, v64, 0
	v_and_b32_e32 v59, 0xffff0000, v205
	v_fmac_f32_e32 v64, v65, v65
	v_pk_fma_f32 v[50:51], v[50:51], s[14:15], v[58:59]
	v_fmac_f32_e32 v64, v50, v50
	v_cvt_pk_bf16_f32 v49, v50, v51
	v_fmac_f32_e32 v64, v51, v51
	v_lshlrev_b32_e32 v50, 16, v206
	v_and_b32_e32 v51, 0xffff0000, v206
	v_pk_fma_f32 v[44:45], v[44:45], s[14:15], v[50:51]
	v_fmac_f32_e32 v64, v44, v44
	v_cvt_pk_bf16_f32 v50, v44, v45
	v_fmac_f32_e32 v64, v45, v45
	v_lshlrev_b32_e32 v44, 16, v207
	v_and_b32_e32 v45, 0xffff0000, v207
	v_pk_fma_f32 v[44:45], v[46:47], s[14:15], v[44:45]
	v_add_co_u32_e32 v46, vcc, s2, v144
	v_fmac_f32_e32 v64, v44, v44
	v_cvt_pk_bf16_f32 v51, v44, v45
	v_fmac_f32_e32 v64, v45, v45
	v_lshlrev_b32_e32 v44, 16, v200
	v_and_b32_e32 v45, 0xffff0000, v200
	v_pk_fma_f32 v[44:45], v[40:41], s[14:15], v[44:45]
	v_addc_co_u32_e32 v47, vcc, 0, v145, vcc
	v_fmac_f32_e32 v64, v44, v44
	v_cvt_pk_bf16_f32 v40, v44, v45
	v_fmac_f32_e32 v64, v45, v45
	v_lshlrev_b32_e32 v44, 16, v201
	v_and_b32_e32 v45, 0xffff0000, v201
	v_pk_fma_f32 v[42:43], v[42:43], s[14:15], v[44:45]
	s_mov_b32 s2, 0xb0000
	v_fmac_f32_e32 v64, v42, v42
	v_cvt_pk_bf16_f32 v41, v42, v43
	v_fmac_f32_e32 v64, v43, v43
	v_lshlrev_b32_e32 v42, 16, v202
	v_and_b32_e32 v43, 0xffff0000, v202
	v_pk_fma_f32 v[36:37], v[36:37], s[14:15], v[42:43]
	v_fmac_f32_e32 v64, v36, v36
	v_cvt_pk_bf16_f32 v42, v36, v37
	v_fmac_f32_e32 v64, v37, v37
	v_lshlrev_b32_e32 v36, 16, v203
	v_and_b32_e32 v37, 0xffff0000, v203
	v_pk_fma_f32 v[36:37], v[38:39], s[14:15], v[36:37]
	s_nop 0
	v_cvt_pk_bf16_f32 v43, v36, v37
	global_store_dwordx4 v[62:63], v[48:51], off offset:-2048
	global_store_dwordx4 v[62:63], v[40:43], off offset:2048
	s_nop 0
	v_fmac_f32_e32 v64, v36, v36
	v_fmac_f32_e32 v64, v37, v37
	ds_bpermute_b32 v36, v153, v64
	s_waitcnt lgkmcnt(0)
	v_add_f32_e32 v36, v64, v36
	ds_bpermute_b32 v37, v152, v36
	s_waitcnt vmcnt(14)
	v_lshlrev_b32_e32 v48, 16, v216
	v_and_b32_e32 v49, 0xffff0000, v216
	v_pk_fma_f32 v[48:49], v[32:33], s[14:15], v[48:49]
	v_lshlrev_b32_e32 v42, 16, v217
	v_cvt_pk_bf16_f32 v32, v48, v49
	v_fma_f32 v48, v48, v48, 0
	v_and_b32_e32 v43, 0xffff0000, v217
	v_fmac_f32_e32 v48, v49, v49
	v_pk_fma_f32 v[34:35], v[34:35], s[14:15], v[42:43]
	v_fmac_f32_e32 v48, v34, v34
	v_cvt_pk_bf16_f32 v33, v34, v35
	v_fmac_f32_e32 v48, v35, v35
	v_lshlrev_b32_e32 v34, 16, v218
	v_and_b32_e32 v35, 0xffff0000, v218
	v_pk_fma_f32 v[28:29], v[28:29], s[14:15], v[34:35]
	v_fmac_f32_e32 v48, v28, v28
	v_cvt_pk_bf16_f32 v34, v28, v29
	v_fmac_f32_e32 v48, v29, v29
	v_lshlrev_b32_e32 v28, 16, v219
	v_and_b32_e32 v29, 0xffff0000, v219
	v_pk_fma_f32 v[28:29], v[30:31], s[14:15], v[28:29]
	v_fmac_f32_e32 v48, v28, v28
	v_cvt_pk_bf16_f32 v35, v28, v29
	v_fmac_f32_e32 v48, v29, v29
	v_lshlrev_b32_e32 v28, 16, v212
	v_and_b32_e32 v29, 0xffff0000, v212
	v_pk_fma_f32 v[28:29], v[24:25], s[14:15], v[28:29]
	v_fmac_f32_e32 v48, v28, v28
	v_cvt_pk_bf16_f32 v24, v28, v29
	v_fmac_f32_e32 v48, v29, v29
	v_lshlrev_b32_e32 v28, 16, v213
	v_and_b32_e32 v29, 0xffff0000, v213
	v_pk_fma_f32 v[26:27], v[26:27], s[14:15], v[28:29]
	v_add_co_u32_e32 v28, vcc, s2, v144
	v_fmac_f32_e32 v48, v26, v26
	v_cvt_pk_bf16_f32 v25, v26, v27
	v_fmac_f32_e32 v48, v27, v27
	v_lshlrev_b32_e32 v26, 16, v214
	v_and_b32_e32 v27, 0xffff0000, v214
	v_pk_fma_f32 v[20:21], v[20:21], s[14:15], v[26:27]
	v_addc_co_u32_e32 v29, vcc, 0, v145, vcc
	v_fmac_f32_e32 v48, v20, v20
	v_cvt_pk_bf16_f32 v26, v20, v21
	v_fmac_f32_e32 v48, v21, v21
	v_lshlrev_b32_e32 v20, 16, v215
	v_and_b32_e32 v21, 0xffff0000, v215
	v_pk_fma_f32 v[20:21], v[22:23], s[14:15], v[20:21]
	v_fmac_f32_e32 v48, v20, v20
	v_fmac_f32_e32 v48, v21, v21
	v_cvt_pk_bf16_f32 v27, v20, v21
	ds_bpermute_b32 v20, v153, v48
	global_store_dwordx4 v[46:47], v[32:35], off offset:-2048
	global_store_dwordx4 v[46:47], v[24:27], off offset:2048
	s_waitcnt lgkmcnt(0)
	v_add_f32_e32 v30, v48, v20
	ds_bpermute_b32 v31, v152, v30
	s_waitcnt vmcnt(14)
	v_lshlrev_b32_e32 v32, 16, v224
	v_and_b32_e32 v33, 0xffff0000, v224
	v_pk_fma_f32 v[32:33], v[16:17], s[14:15], v[32:33]
	v_lshlrev_b32_e32 v24, 16, v225
	v_cvt_pk_bf16_f32 v16, v32, v33
	v_fma_f32 v32, v32, v32, 0
	v_and_b32_e32 v25, 0xffff0000, v225
	v_fmac_f32_e32 v32, v33, v33
	v_pk_fma_f32 v[18:19], v[18:19], s[14:15], v[24:25]
	v_fmac_f32_e32 v32, v18, v18
	v_cvt_pk_bf16_f32 v17, v18, v19
	v_fmac_f32_e32 v32, v19, v19
	v_lshlrev_b32_e32 v18, 16, v226
	v_and_b32_e32 v19, 0xffff0000, v226
	v_pk_fma_f32 v[12:13], v[12:13], s[14:15], v[18:19]
	v_fmac_f32_e32 v32, v12, v12
	v_cvt_pk_bf16_f32 v18, v12, v13
	v_fmac_f32_e32 v32, v13, v13
	v_lshlrev_b32_e32 v12, 16, v227
	v_and_b32_e32 v13, 0xffff0000, v227
	v_pk_fma_f32 v[12:13], v[14:15], s[14:15], v[12:13]
	v_fmac_f32_e32 v32, v12, v12
	v_cvt_pk_bf16_f32 v19, v12, v13
	v_fmac_f32_e32 v32, v13, v13
	v_lshlrev_b32_e32 v12, 16, v220
	v_and_b32_e32 v13, 0xffff0000, v220
	v_pk_fma_f32 v[12:13], v[8:9], s[14:15], v[12:13]
	v_fmac_f32_e32 v32, v12, v12
	v_cvt_pk_bf16_f32 v8, v12, v13
	v_fmac_f32_e32 v32, v13, v13
	v_lshlrev_b32_e32 v12, 16, v221
	v_and_b32_e32 v13, 0xffff0000, v221
	v_pk_fma_f32 v[10:11], v[10:11], s[14:15], v[12:13]
	v_fmac_f32_e32 v32, v10, v10
	v_cvt_pk_bf16_f32 v9, v10, v11
	v_fmac_f32_e32 v32, v11, v11
	v_lshlrev_b32_e32 v10, 16, v222
	v_and_b32_e32 v11, 0xffff0000, v222
	v_pk_fma_f32 v[4:5], v[4:5], s[14:15], v[10:11]
	v_fmac_f32_e32 v32, v4, v4
	v_cvt_pk_bf16_f32 v10, v4, v5
	v_fmac_f32_e32 v32, v5, v5
	v_lshlrev_b32_e32 v4, 16, v223
	v_and_b32_e32 v5, 0xffff0000, v223
	v_pk_fma_f32 v[4:5], v[6:7], s[14:15], v[4:5]
	v_fmac_f32_e32 v32, v4, v4
	v_fmac_f32_e32 v32, v5, v5
	v_cvt_pk_bf16_f32 v11, v4, v5
	ds_bpermute_b32 v4, v153, v32
	global_store_dwordx4 v[28:29], v[16:19], off offset:-2048
	global_store_dwordx4 v[28:29], v[8:11], off offset:2048
	s_waitcnt lgkmcnt(0)
	v_add_f32_e32 v4, v32, v4
	ds_bpermute_b32 v5, v152, v4
	s_and_saveexec_b64 s[2:3], s[38:39]
	v_add_f32_e32 v2, v30, v31
	v_add_f32_e32 v6, v52, v53
	v_add_f32_e32 v7, v94, v95
	v_cndmask_b32_e64 v2, v2, v6, s[42:43]
	v_cndmask_b32_e64 v2, v2, v7, s[40:41]
	s_or_b64 exec, exec, s[2:3]
	v_add_f32_e32 v8, v36, v37
	s_waitcnt lgkmcnt(0)
	v_add_f32_e32 v4, v4, v5
	v_add_f32_e32 v7, v68, v69
	v_cndmask_b32_e64 v4, v4, v8, s[42:43]
	v_add_f32_e32 v6, v100, v101
	v_cndmask_b32_e64 v4, v4, v7, s[40:41]
	v_cndmask_b32_e64 v6, v4, v6, s[36:37]
	v_add_u32_e32 v4, v148, v151
	v_ashrrev_i32_e32 v5, 31, v4
	v_readlane_b32 s2, v252, 45
	v_lshlrev_b64 v[4:5], 7, v[4:5]
	v_readlane_b32 s3, v252, 46
	s_and_b64 vcc, exec, s[44:45]
	s_nop 0
	v_lshl_add_u64 v[4:5], s[2:3], 0, v[4:5]
	s_lshl_b32 s2, s17, 2
	s_ashr_i32 s3, s2, 31
	v_lshl_add_u64 v[4:5], s[2:3], 2, v[4:5]
	v_readlane_b32 s2, v255, 9
	v_readlane_b32 s3, v255, 10
	s_nop 1
	v_lshl_add_u64 v[4:5], v[4:5], 0, s[2:3]
	s_mov_b64 s[2:3], -1
	global_store_dword v[4:5], v2, off
	global_store_dword v[4:5], v6, off offset:2048
	s_cbranch_vccnz .LBB0_820
	s_andn2_b64 vcc, exec, s[12:13]
	s_cbranch_vccnz .LBB0_819
	s_barrier
	s_branch .LBB0_819
